# v007 plus rowwise PLE-input clone: p-row load issued with the x/y loads (one wait per row instead of two)
# speedup vs baseline: 1.0075x; 1.0075x over previous
; __device__ __forceinline__ float bflo(unsigned w) { return __uint_as_float(w << 16); }
; __device__ __forceinline__ float bfhi(unsigned w) { return __uint_as_float(w & 0xffff0000u); }
; __device__ void rowwise_phase(const float* __restrict__ xin, float* __restrict__ xres, const bf16_t* __restrict__ y, const float* __restrict__ w_post, ...
;     ...
;     if (y) {
; #pragma unroll
;       for (int c = 0; c < 2; ++c) { const u32x4 w = __builtin_nontemporal_load((const u32x4*)((const bf16_t*)(xres + (size_t)row * 1024) + c * 512 + lane * 8));
; #pragma unroll
;         for (int i = 0; i < 4; ++i) { x[c * 8 + 2 * i] = bflo(w[i]); x[c * 8 + 2 * i + 1] = bfhi(w[i]); } }
;     } else {
; #pragma unroll
;       for (int c = 0; c < 2; ++c) { const float* xp = xin + (size_t)row * 1024 + c * 512 + lane * 8;
;         const f32x4 a = __builtin_nontemporal_load((const f32x4*)xp), b = __builtin_nontemporal_load((const f32x4*)(xp + 4));
;         x[c * 8 + 0] = a[0]; x[c * 8 + 1] = a[1]; x[c * 8 + 2] = a[2]; x[c * 8 + 3] = a[3]; x[c * 8 + 4] = b[0]; x[c * 8 + 5] = b[1]; x[c * 8 + 6] = b[2]; x[c * 8 + 7] = b[3]; }
;     }
;     if (y) {
;       float yv[16]; float ss = 0.f;
; #pragma unroll
;       for (int c = 0; c < 2; ++c) { const u32x4 w = __builtin_nontemporal_load((const u32x4*)(y + (size_t)row * 1024 + c * 512 + lane * 8));
; #pragma unroll
;         for (int i = 0; i < 4; ++i) { yv[c * 8 + 2 * i] = bflo(w[i]); yv[c * 8 + 2 * i + 1] = bfhi(w[i]); } }
;     ...
;       if (p_src) { const f32x4 pv = __builtin_nontemporal_load((const f32x4*)(p_src + (size_t)row * 256 + lane * 4));
.LBB0_75:
	v_ashrrev_i32_e32 v19, 31, v18
	v_lshlrev_b64 v[30:31], 11, v[18:19]
	v_lshl_add_u64 v[30:31], v[22:23], 0, v[30:31]
	global_load_dwordx4 v[40:43], v[30:31], off nt
	global_load_dwordx4 v[44:47], v[30:31], off offset:1024 nt
	v_lshlrev_b64 v[30:31], 12, v[18:19]
	v_lshl_add_u64 v[30:31], v[20:21], 0, v[30:31]
	global_load_dwordx4 v[48:51], v[30:31], off nt
	global_load_dwordx4 v[52:55], v[30:31], off offset:1024 nt
	s_and_b64 vcc, exec, s[12:13]
	s_cbranch_vccz .Lrw_nop
	v_lshlrev_b64 v[84:85], 10, v[18:19]
	v_lshl_add_u64 v[84:85], v[26:27], 0, v[84:85]
	global_load_dwordx4 v[80:83], v[84:85], off nt
; __device__ __forceinline__ float bflo(unsigned w) { return __uint_as_float(w << 16); }
; __device__ void rowwise_phase(const float* __restrict__ xin, float* __restrict__ xres, const bf16_t* __restrict__ y, const float* __restrict__ w_post, ...
;     ...
;     if (y) {
;       float yv[16]; float ss = 0.f;
; #pragma unroll
;       for (int c = 0; c < 2; ++c) { const u32x4 w = __builtin_nontemporal_load((const u32x4*)(y + (size_t)row * 1024 + c * 512 + lane * 8));
; #pragma unroll
;         for (int i = 0; i < 4; ++i) { yv[c * 8 + 2 * i] = bflo(w[i]); yv[c * 8 + 2 * i + 1] = bfhi(w[i]); } }
; #pragma unroll
;       for (int i = 0; i < 16; ++i) ss += yv[i] * yv[i];
;       ss = wave_sum(ss);
;       const float rs = rsqrtf(ss * (1.f / 1024.f) + EPS);
; #pragma unroll
;       for (int c = 0; c < 2; ++c) { const float* wp = w_post + c * 512 + lane * 8; const f32x4 a = *(const f32x4*)wp, b = *(const f32x4*)(wp + 4);
;         x[c * 8 + 0] += yv[c * 8 + 0] * rs * a[0]; x[c * 8 + 1] += yv[c * 8 + 1] * rs * a[1]; x[c * 8 + 2] += yv[c * 8 + 2] * rs * a[2]; x[c * 8 + 3] += yv[c * 8 + 3] * rs * a[3];
;         x[c * 8 + 4] += yv[c * 8 + 4] * rs * b[0]; x[c * 8 + 5] += yv[c * 8 + 5] * rs * b[1]; x[c * 8 + 6] += yv[c * 8 + 6] * rs * b[2]; x[c * 8 + 7] += yv[c * 8 + 7] * rs * b[3]; }
;     }
;     if (final_f32) {
; #pragma unroll
;       for (int c = 0; c < 2; ++c) { float* xp = xres + (size_t)row * 1024 + c * 512 + lane * 8;
;         __builtin_nontemporal_store((f32x4){x[c * 8 + 0], x[c * 8 + 1], x[c * 8 + 2], x[c * 8 + 3]}, (f32x4*)xp); __builtin_nontemporal_store((f32x4){x[c * 8 + 4], x[c * 8 + 5], x[c * 8 + 6], x[c * 8 + 7]}, (f32x4*)(xp + 4)); }
;     } else {
; #pragma unroll
;       for (int c = 0; c < 2; ++c) { u32x4 w;
; #pragma unroll
;         for (int i = 0; i < 4; ++i) w[i] = cvtpk(x[c * 8 + 2 * i], x[c * 8 + 2 * i + 1]);
;         __builtin_nontemporal_store(w, (u32x4*)((bf16_t*)(xres + (size_t)row * 1024) + c * 512 + lane * 8)); }
;     }
;     if (do_next) {
;       float s2 = 0.f;
; #pragma unroll
;       for (int i = 0; i < 16; ++i) s2 += x[i] * x[i];
;       s2 = wave_sum(s2);
;       const float r2 = rsqrtf(s2 * (1.f / 1024.f) + EPS);
; #pragma unroll
;       for (int c = 0; c < 2; ++c) { float wv[8];
;         if (w_next) { const float* wp = w_next + c * 512 + lane * 8; const f32x4 a = *(const f32x4*)wp, b = *(const f32x4*)(wp + 4);
.Lrw_nop:
	s_movk_i32 s0, 0x500
	s_waitcnt vmcnt(0)
	v_lshlrev_b32_e32 v58, 16, v40
	v_and_b32_e32 v59, 0xffff0000, v40
	v_lshlrev_b32_e32 v32, 16, v43
	v_and_b32_e32 v33, 0xffff0000, v43
	v_lshlrev_b32_e32 v56, 16, v42
	v_and_b32_e32 v57, 0xffff0000, v42
	v_lshlrev_b32_e32 v42, 16, v41
	v_and_b32_e32 v43, 0xffff0000, v41
	v_pk_mul_f32 v[68:69], v[58:59], v[58:59]
	v_pk_mul_f32 v[66:67], v[42:43], v[42:43]
	v_add_f32_e32 v39, v68, v69
	v_add_f32_e32 v39, v66, v39
	v_pk_mul_f32 v[64:65], v[56:57], v[56:57]
	v_add_f32_e32 v39, v67, v39
	v_add_f32_e32 v39, v64, v39
	v_lshlrev_b32_e32 v40, 16, v47
	v_and_b32_e32 v41, 0xffff0000, v47
	v_lshlrev_b32_e32 v60, 16, v46
	v_and_b32_e32 v61, 0xffff0000, v46
	v_lshlrev_b32_e32 v46, 16, v45
	v_and_b32_e32 v47, 0xffff0000, v45
	v_lshlrev_b32_e32 v62, 16, v44
	v_and_b32_e32 v63, 0xffff0000, v44
	v_pk_mul_f32 v[44:45], v[32:33], v[32:33]
	v_add_f32_e32 v39, v65, v39
	v_add_f32_e32 v39, v44, v39
	v_pk_mul_f32 v[76:77], v[62:63], v[62:63]
	v_add_f32_e32 v39, v45, v39
	v_add_f32_e32 v39, v76, v39
	v_pk_mul_f32 v[74:75], v[46:47], v[46:47]
	v_add_f32_e32 v39, v77, v39
	v_add_f32_e32 v39, v74, v39
	v_pk_mul_f32 v[72:73], v[60:61], v[60:61]
	v_add_f32_e32 v39, v75, v39
	v_add_f32_e32 v39, v72, v39
	v_pk_mul_f32 v[70:71], v[40:41], v[40:41]
	v_add_f32_e32 v39, v73, v39
	v_add_f32_e32 v39, v70, v39
	v_add_f32_e32 v39, v71, v39
	ds_bpermute_b32 v44, v0, v39
	v_lshlrev_b32_e32 v64, 16, v50
	v_and_b32_e32 v65, 0xffff0000, v50
	v_lshlrev_b32_e32 v50, 16, v49
	v_and_b32_e32 v67, 0xffff0000, v48
	s_waitcnt lgkmcnt(0)
	v_add_f32_e32 v39, v39, v44
	ds_bpermute_b32 v44, v34, v39
	v_and_b32_e32 v71, 0xffff0000, v52
	v_and_b32_e32 v69, 0xffff0000, v54
	s_waitcnt lgkmcnt(0)
	v_add_f32_e32 v39, v39, v44
	ds_bpermute_b32 v45, v35, v39
	v_lshlrev_b32_e32 v44, 16, v51
	s_waitcnt lgkmcnt(0)
	v_add_f32_e32 v39, v39, v45
	ds_bpermute_b32 v66, v36, v39
	v_and_b32_e32 v45, 0xffff0000, v51
	v_and_b32_e32 v51, 0xffff0000, v49
	v_and_b32_e32 v49, 0xffff0000, v55
	s_waitcnt lgkmcnt(0)
	v_add_f32_e32 v39, v39, v66
	ds_bpermute_b32 v68, v37, v39
	v_lshlrev_b32_e32 v66, 16, v48
	v_lshlrev_b32_e32 v48, 16, v55
	s_waitcnt lgkmcnt(0)
	v_add_f32_e32 v39, v39, v68
	ds_bpermute_b32 v70, v38, v39
	v_lshlrev_b32_e32 v68, 16, v54
	v_lshlrev_b32_e32 v54, 16, v53
	s_waitcnt lgkmcnt(0)
	v_add_f32_e32 v39, v39, v70
	v_fmamk_f32 v39, v39, 0x3a800000, v171
	v_mul_f32_e32 v55, 0x4b800000, v39
	v_cmp_gt_f32_e32 vcc, s63, v39
	v_lshlrev_b32_e32 v70, 16, v52
	s_nop 0
	v_cndmask_b32_e32 v39, v39, v55, vcc
	v_rsq_f32_e32 v39, v39
	v_and_b32_e32 v55, 0xffff0000, v53
	v_mul_f32_e32 v52, 0x45800000, v39
	v_cndmask_b32_e32 v52, v39, v52, vcc
	v_pk_mul_f32 v[58:59], v[52:53], v[58:59] op_sel_hi:[0,1]
	v_pk_mul_f32 v[42:43], v[52:53], v[42:43] op_sel_hi:[0,1]
	v_pk_mul_f32 v[56:57], v[52:53], v[56:57] op_sel_hi:[0,1]
	v_pk_mul_f32 v[32:33], v[52:53], v[32:33] op_sel_hi:[0,1]
	v_pk_mul_f32 v[62:63], v[52:53], v[62:63] op_sel_hi:[0,1]
	v_pk_mul_f32 v[46:47], v[52:53], v[46:47] op_sel_hi:[0,1]
	v_pk_mul_f32 v[60:61], v[52:53], v[60:61] op_sel_hi:[0,1]
	v_pk_mul_f32 v[40:41], v[52:53], v[40:41] op_sel_hi:[0,1]
	v_pk_fma_f32 v[52:53], v[2:3], v[58:59], v[66:67]
	v_pk_fma_f32 v[50:51], v[4:5], v[42:43], v[50:51]
	v_pk_fma_f32 v[58:59], v[8:9], v[32:33], v[44:45]
	v_pk_mul_f32 v[32:33], v[52:53], v[52:53]
	v_pk_fma_f32 v[48:49], v[16:17], v[40:41], v[48:49]
	v_pk_mul_f32 v[40:41], v[50:51], v[50:51]
	v_add_f32_e32 v32, v32, v33
	v_pk_fma_f32 v[56:57], v[6:7], v[56:57], v[64:65]
	v_add_f32_e32 v32, v40, v32
	v_pk_mul_f32 v[42:43], v[56:57], v[56:57]
	v_add_f32_e32 v32, v41, v32
	v_add_f32_e32 v32, v42, v32
	v_pk_mul_f32 v[44:45], v[58:59], v[58:59]
	v_add_f32_e32 v32, v43, v32
	v_pk_fma_f32 v[62:63], v[10:11], v[62:63], v[70:71]
	v_add_f32_e32 v32, v44, v32
	v_pk_fma_f32 v[54:55], v[12:13], v[46:47], v[54:55]
	v_pk_mul_f32 v[46:47], v[62:63], v[62:63]
	v_add_f32_e32 v32, v45, v32
	v_add_f32_e32 v32, v46, v32
	v_pk_mul_f32 v[64:65], v[54:55], v[54:55]
	v_add_f32_e32 v32, v47, v32
	v_pk_fma_f32 v[60:61], v[14:15], v[60:61], v[68:69]
	v_add_f32_e32 v32, v64, v32
	v_pk_mul_f32 v[66:67], v[60:61], v[60:61]
	v_add_f32_e32 v32, v65, v32
	v_add_f32_e32 v32, v66, v32
	v_pk_mul_f32 v[68:69], v[48:49], v[48:49]
	v_add_f32_e32 v32, v67, v32
	v_add_f32_e32 v32, v68, v32
	v_add_f32_e32 v32, v69, v32
	ds_bpermute_b32 v33, v0, v32
	v_cvt_pk_bf16_f32 v41, v50, v51
	v_cvt_pk_bf16_f32 v42, v56, v57
	v_cvt_pk_bf16_f32 v44, v62, v63
	v_cvt_pk_bf16_f32 v45, v54, v55
	s_waitcnt lgkmcnt(0)
	v_add_f32_e32 v32, v32, v33
	ds_bpermute_b32 v33, v34, v32
	v_cvt_pk_bf16_f32 v46, v60, v61
	s_andn2_b64 vcc, exec, s[12:13]
	s_waitcnt lgkmcnt(0)
	v_add_f32_e32 v32, v32, v33
	ds_bpermute_b32 v33, v35, v32
	s_waitcnt lgkmcnt(0)
	v_add_f32_e32 v39, v32, v33
	ds_bpermute_b32 v40, v36, v39
	v_mad_i64_i32 v[32:33], s[0:1], v18, s0, 0
	v_lshl_add_u64 v[64:65], v[32:33], 1, v[24:25]
	s_waitcnt lgkmcnt(0)
	v_add_f32_e32 v39, v39, v40
	ds_bpermute_b32 v43, v37, v39
	v_cvt_pk_bf16_f32 v40, v52, v53
	s_waitcnt lgkmcnt(0)
	v_add_f32_e32 v39, v39, v43
	ds_bpermute_b32 v47, v38, v39
	v_cvt_pk_bf16_f32 v43, v58, v59
	s_waitcnt lgkmcnt(0)
	v_add_f32_e32 v39, v39, v47
	v_fmamk_f32 v39, v39, 0x3a800000, v171
	v_mul_f32_e32 v47, 0x4b800000, v39
	v_cmp_gt_f32_e64 s[0:1], s63, v39
	s_nop 1
	v_cndmask_b32_e64 v39, v39, v47, s[0:1]
	v_rsq_f32_e32 v39, v39
	v_cvt_pk_bf16_f32 v47, v48, v49
	global_store_dwordx4 v[30:31], v[40:43], off nt
	global_store_dwordx4 v[30:31], v[44:47], off offset:1024 nt
	v_mul_f32_e32 v30, 0x45800000, v39
	v_cndmask_b32_e64 v30, v39, v30, s[0:1]
	v_pk_mul_f32 v[40:41], v[52:53], v[30:31] op_sel_hi:[1,0]
	v_pk_mul_f32 v[42:43], v[50:51], v[30:31] op_sel_hi:[1,0]
	v_pk_mul_f32 v[44:45], v[56:57], v[30:31] op_sel_hi:[1,0]
	v_pk_mul_f32 v[46:47], v[58:59], v[30:31] op_sel_hi:[1,0]
	v_pk_mul_f32 v[50:51], v[62:63], v[30:31] op_sel_hi:[1,0]
	v_pk_mul_f32 v[52:53], v[54:55], v[30:31] op_sel_hi:[1,0]
	v_pk_mul_f32 v[54:55], v[60:61], v[30:31] op_sel_hi:[1,0]
	v_pk_mul_f32 v[30:31], v[48:49], v[30:31] op_sel_hi:[1,0]
	v_cvt_pk_bf16_f32 v40, v40, v41
	v_cvt_pk_bf16_f32 v41, v42, v43
	v_cvt_pk_bf16_f32 v42, v44, v45
	v_cvt_pk_bf16_f32 v43, v46, v47
	v_cvt_pk_bf16_f32 v44, v50, v51
	v_cvt_pk_bf16_f32 v45, v52, v53
	v_cvt_pk_bf16_f32 v46, v54, v55
	v_cvt_pk_bf16_f32 v47, v30, v31
	global_store_dwordx4 v[64:65], v[40:43], off
	global_store_dwordx4 v[64:65], v[44:47], off offset:1024
	s_cbranch_vccnz .LBB0_74
	v_lshl_add_u64 v[32:33], v[32:33], 1, v[28:29]
	v_cvt_pk_bf16_f32 v30, v80, v81
	v_cvt_pk_bf16_f32 v31, v82, v83
	global_store_dwordx2 v[32:33], v[30:31], off
	s_branch .LBB0_74
